# P5 static s_setprio 1 for waves 4-7 (lagging half) before the attention loop, reset at exit
# baseline (speedup 1.0000x reference)
; #define SBAR() __builtin_amdgcn_sched_barrier(0)
; #define VMW() asm volatile("s_waitcnt vmcnt(0)" ::: "memory")
; #define SLOAD_H(Kp, Vp, k0) do { S.st_v0 = load8(ROW(Vp, k0, sr)); S.st_v1 = load8(ROW(Vp, k0, 32 + sr));              \
;                          S.st_k0 = load8(ROW(Kp, k0, sr)); S.st_k1 = load8(ROW(Kp, k0, 32 + sr)); } while (0)
; #define SWRITE_HV(bf) do { *(bf16x8*)(V_lds + (bf) * SHM_V + vst0) = S.st_v0; *(bf16x8*)(V_lds + (bf) * SHM_V + vst1) = S.st_v1; } while (0)
; #define SWRITE_H(bf) do { SWRITE_HV(bf); SWRITE_HK(bf); } while (0)
; #define MASKT(P0_, P1_) sel_mask_tile(P0_, P1_, mw.x, mw.y, hi)
; template <int KB>
; __device__ __forceinline__ void qkt(f32x16& p0, f32x16& p1, const char* K_lds, int r32, int hi, const bf16x8* qr) {
;     p0 = f32x16{}; p1 = f32x16{};
;     const char* kb[4];
; #pragma unroll
;     for (int dd = 0; dd < 4; ++dd) kb[dd] = K_lds + KB * SHM_K + KSWZ(r32, (dd * 16 + hi * 8) * 2);
; #pragma unroll
;     for (int d0 = 0; d0 < 8; ++d0) { const char* a = kb[d0 & 3] + (d0 >> 2) * 128;
;         bf16x8 b0 = *reinterpret_cast<const bf16x8*>(a);
;         bf16x8 b1 = *reinterpret_cast<const bf16x8*>(a + 32 * 256);
;         p0 = __builtin_amdgcn_mfma_f32_32x32x16_bf16(b0, qr[d0], p0, 0, 0, 0);
;         p1 = __builtin_amdgcn_mfma_f32_32x32x16_bf16(b1, qr[d0], p1, 0, 0, 0); }
; __device__ __forceinline__ void attn_block(const BlockRef& cur, const BlockRef& nxt, char* lds, Seam& S) {
;     ...
;     SWRITE_HV(0); SBAR();
;     mw = LDMASK(0);
;     if (NT > 1) { SLOAD_H(Kh, Vh, KBASE(1)); }
;     SBAR(); qkt<0>(pA0, pA1, K_lds, r32, hi, S.qr);
;     MASKT(pA0, pA1); partialSM(pA0, pA1, m_reg, mnA, alA);
;     if (NT > 1) { VMW(); SWRITE_H(1); }
;     __syncthreads();
.LBB0_1298:
	v_readfirstlane_b32 s83, v0
	s_lshr_b32 s12, s38, 6
	s_or_b32 s81, s12, 3
	s_and_b32 s12, s83, 0x3fffffc0
	s_lshl_b32 s12, s12, 2
	s_add_i32 s84, s12, 0
	s_lshr_b32 s12, s83, 1
	s_and_b32 s12, s12, 0x7fffffe0
	v_and_b32_e32 v88, 31, v0
	v_or_b32_e32 v186, s12, v88
	s_mov_b32 s82, 1
	v_lshlrev_b32_e32 v165, 9, v186
	s_add_i32 s84, s84, 0x10000
	s_waitcnt vmcnt(1)
	ds_write_b128 v197, v[130:133]
	s_waitcnt vmcnt(0)
	ds_write_b128 v198, v[134:137]
	v_mov_b32_e32 v183, v167
	v_lshl_add_u64 v[2:3], s[70:71], 0, v[182:183]
	v_mov_b32_e32 v177, v167
	v_mov_b32_e32 v185, v167
	v_lshl_add_u64 v[2:3], v[2:3], 0, v[176:177]
	v_lshl_add_u64 v[4:5], s[70:71], 0, v[184:185]
	global_load_dwordx2 v[86:87], v165, s[68:69]
	v_lshl_add_u64 v[4:5], v[4:5], 0, v[176:177]
	global_load_dwordx4 v[50:53], v[2:3], off
	global_load_dwordx4 v[54:57], v[4:5], off
	v_lshl_add_u64 v[2:3], s[6:7], 0, v[182:183]
	v_lshl_add_u64 v[2:3], v[2:3], 0, v[176:177]
	v_lshl_add_u64 v[4:5], s[6:7], 0, v[184:185]
	v_lshl_add_u64 v[4:5], v[4:5], 0, v[176:177]
	global_load_dwordx4 v[58:61], v[2:3], off
	global_load_dwordx4 v[62:65], v[4:5], off
	ds_read_b128 v[2:5], v199 offset:32768
	ds_read_b128 v[6:9], v199 offset:32896
	s_mov_b32 s36, s13
	s_mov_b32 s37, s13
	s_mov_b32 s38, s13
	s_waitcnt lgkmcnt(1)
	v_mfma_f32_32x32x16_bf16 v[34:49], v[2:5], v[126:129], 0
	ds_read_b128 v[2:5], v199 offset:40960
	ds_read_b128 v[10:13], v199 offset:41088
	s_mov_b32 s39, s13
	s_mov_b32 s40, s13
	s_mov_b32 s41, s13
	s_mov_b32 s42, s13
	s_mov_b32 s43, s13
	s_mov_b32 s44, s13
	s_waitcnt lgkmcnt(1)
	v_mfma_f32_32x32x16_bf16 v[18:33], v[2:5], v[126:129], 0
	ds_read_b128 v[2:5], v200 offset:32768
	ds_read_b128 v[14:17], v200 offset:32896
	s_mov_b32 s45, s13
	s_mov_b32 s46, s13
	s_mov_b32 s47, s13
	s_mov_b32 s48, s13
	s_mov_b32 s49, s13
	s_mov_b32 s50, s13
	s_waitcnt lgkmcnt(1)
	v_mfma_f32_32x32x16_bf16 v[34:49], v[2:5], v[122:125], v[34:49]
	ds_read_b128 v[2:5], v200 offset:40960
	ds_read_b128 v[66:69], v200 offset:41088
	s_mov_b32 s51, s13
	v_lshl_add_u32 v185, v88, 2, s84
	v_lshl_add_u32 v183, v163, 2, s84
	v_add_u32_e32 v188, v170, v252
	s_mov_b64 s[16:17], s[70:71]
	s_mov_b64 s[100:101], s[6:7]
	v_mov_b32_e32 v205, 0
	s_waitcnt lgkmcnt(1)
	v_mfma_f32_32x32x16_bf16 v[18:33], v[2:5], v[122:125], v[18:33]
	ds_read_b128 v[2:5], v201 offset:32768
	ds_read_b128 v[70:73], v201 offset:32896
	s_waitcnt lgkmcnt(1)
	v_mfma_f32_32x32x16_bf16 v[34:49], v[2:5], v[118:121], v[34:49]
	ds_read_b128 v[2:5], v201 offset:40960
	ds_read_b128 v[74:77], v201 offset:41088
	s_waitcnt lgkmcnt(1)
	v_mfma_f32_32x32x16_bf16 v[18:33], v[2:5], v[118:121], v[18:33]
	ds_read_b128 v[2:5], v202 offset:32768
	ds_read_b128 v[78:81], v202 offset:32896
	s_waitcnt lgkmcnt(1)
	v_mfma_f32_32x32x16_bf16 v[34:49], v[2:5], v[114:117], v[34:49]
	ds_read_b128 v[2:5], v202 offset:40960
	ds_read_b128 v[82:85], v202 offset:41088
	s_waitcnt vmcnt(0)
	s_waitcnt vmcnt(3)
	ds_write_b128 v197, v[50:53] offset:16384
	s_waitcnt vmcnt(2)
	ds_write_b128 v198, v[54:57] offset:16384
	s_waitcnt vmcnt(1)
	ds_write_b128 v204, v[58:61] offset:49152
	s_waitcnt vmcnt(0)
	ds_write_b128 v204, v[62:65] offset:57344
	s_waitcnt lgkmcnt(0)
	s_barrier
; __device__ __forceinline__ void partialSM(f32x16& p0, f32x16& p1, float& m_reg, float& mn, float& alpha) {
;     float pmax = p0[0];
; #pragma unroll
;     for (int r = 1; r < 16; ++r) pmax = fmaxf(pmax, p0[r]);
; #pragma unroll
;     for (int r = 0; r < 16; ++r) pmax = fmaxf(pmax, p1[r]);
;     { auto rr = __builtin_amdgcn_permlane32_swap(__float_as_uint(pmax), __float_as_uint(pmax), false, false);
;       pmax = fmaxf(__uint_as_float(rr[0]), __uint_as_float(rr[1])); }
;     constexpr float C2 = 1.4426950408889634f * SCALE;
;     if (__builtin_expect(__all((pmax - m_reg) * SCALE <= THR), 1)) { mn = m_reg; alpha = 1.f; }
;     else { mn = fmaxf(m_reg, pmax); alpha = __builtin_amdgcn_exp2f((m_reg - mn) * C2); m_reg = mn; }
;     const float mnL = -mn * C2;
; #pragma unroll
;     for (int r = 0; r < 16; ++r) p0[r] = fmaf(p0[r], C2, mnL);
; #pragma unroll
;     for (int r = 0; r < 16; ++r) p1[r] = fmaf(p1[r], C2, mnL);
; #pragma unroll
;     for (int r = 0; r < 16; ++r) p0[r] = __builtin_amdgcn_exp2f(p0[r]);
	v_mfma_f32_32x32x16_bf16 v[34:49], v[6:9], v[110:113], v[34:49]
	v_mfma_f32_32x32x16_bf16 v[18:33], v[2:5], v[114:117], v[18:33]
	v_mfma_f32_32x32x16_bf16 v[34:49], v[14:17], v[106:109], v[34:49]
	v_mfma_f32_32x32x16_bf16 v[18:33], v[10:13], v[110:113], v[18:33]
	v_mov_b64_e32 v[2:3], s[36:37]
	v_mov_b64_e32 v[4:5], s[38:39]
	v_mov_b64_e32 v[6:7], s[40:41]
	v_mov_b64_e32 v[8:9], s[42:43]
	v_mov_b64_e32 v[10:11], s[44:45]
	v_mov_b64_e32 v[12:13], s[46:47]
	v_mov_b64_e32 v[14:15], s[48:49]
	v_mfma_f32_32x32x16_bf16 v[34:49], v[70:73], v[102:105], v[34:49]
	v_mov_b64_e32 v[16:17], s[50:51]
	v_mov_b64_e32 v[64:65], v[16:17]
	v_mov_b64_e32 v[62:63], v[14:15]
	v_mov_b64_e32 v[60:61], v[12:13]
	v_mov_b64_e32 v[58:59], v[10:11]
	v_mov_b64_e32 v[56:57], v[8:9]
	v_mov_b64_e32 v[54:55], v[6:7]
	v_mfma_f32_32x32x16_bf16 v[18:33], v[66:69], v[106:109], v[18:33]
	v_lshrrev_b32_e32 v66, v163, v86
	v_bfe_i32 v68, v66, 0, 1
	v_lshrrev_b32_e32 v67, v163, v87
	v_bfe_i32 v69, v67, 0, 1
	v_bfe_i32 v70, v67, 2, 1
	v_bfe_i32 v71, v67, 3, 1
	v_bfe_i32 v72, v67, 8, 1
	v_mfma_f32_32x32x16_bf16 v[34:49], v[78:81], v[98:101], v[34:49]
	v_bfe_i32 v73, v67, 9, 1
	v_bfe_i32 v78, v67, 18, 1
	v_bfe_i32 v79, v67, 19, 1
	v_bfe_i32 v80, v67, 24, 1
	v_bfe_i32 v81, v67, 25, 1
	v_mov_b64_e32 v[52:53], v[4:5]
	v_mov_b64_e32 v[50:51], v[2:3]
	v_mfma_f32_32x32x16_bf16 v[18:33], v[74:77], v[102:105], v[18:33]
	s_nop 3
	v_bitop3_b32 v68, v34, s74, v68 bitop3:0xe4
	v_bfe_i32 v34, v66, 1, 1
	v_bitop3_b32 v35, v35, s74, v34 bitop3:0xe4
	v_bfe_i32 v34, v66, 2, 1
	v_bitop3_b32 v36, v36, s74, v34 bitop3:0xe4
	v_bfe_i32 v34, v66, 3, 1
	v_bitop3_b32 v37, v37, s74, v34 bitop3:0xe4
	v_bfe_i32 v34, v66, 8, 1
	v_bitop3_b32 v38, v38, s74, v34 bitop3:0xe4
	v_bfe_i32 v34, v66, 9, 1
	v_bitop3_b32 v39, v39, s74, v34 bitop3:0xe4
	v_bfe_i32 v34, v66, 10, 1
	v_bitop3_b32 v40, v40, s74, v34 bitop3:0xe4
	v_bfe_i32 v34, v66, 11, 1
	v_mfma_f32_32x32x16_bf16 v[18:33], v[82:85], v[98:101], v[18:33]
	v_bitop3_b32 v41, v41, s74, v34 bitop3:0xe4
	v_bfe_i32 v34, v66, 16, 1
	v_bitop3_b32 v42, v42, s74, v34 bitop3:0xe4
	v_bfe_i32 v34, v66, 17, 1
	v_bitop3_b32 v43, v43, s74, v34 bitop3:0xe4
	v_bfe_i32 v34, v66, 18, 1
	v_bitop3_b32 v44, v44, s74, v34 bitop3:0xe4
	v_bfe_i32 v34, v66, 19, 1
	v_bitop3_b32 v45, v45, s74, v34 bitop3:0xe4
	v_bfe_i32 v34, v66, 24, 1
	v_bitop3_b32 v46, v46, s74, v34 bitop3:0xe4
	v_bfe_i32 v34, v66, 25, 1
	v_bitop3_b32 v47, v47, s74, v34 bitop3:0xe4
	v_bfe_i32 v34, v66, 26, 1
	v_bitop3_b32 v48, v48, s74, v34 bitop3:0xe4
	v_bfe_i32 v34, v66, 27, 1
	v_bitop3_b32 v18, v18, s74, v69 bitop3:0xe4
	v_bfe_i32 v69, v67, 1, 1
	v_bfe_i32 v74, v67, 10, 1
	v_bfe_i32 v75, v67, 11, 1
	v_bfe_i32 v76, v67, 16, 1
	v_bfe_i32 v77, v67, 17, 1
	v_bfe_i32 v82, v67, 26, 1
	v_bfe_i32 v66, v67, 27, 1
	v_bitop3_b32 v49, v49, s74, v34 bitop3:0xe4
	v_max_f32_e32 v34, v35, v35
	v_max_f32_e32 v67, v68, v68
	v_max_f32_e32 v34, v67, v34
	v_max3_f32 v34, v34, v36, v37
	v_max3_f32 v34, v34, v38, v39
	v_max3_f32 v34, v34, v40, v41
	v_max3_f32 v34, v34, v42, v43
	v_max3_f32 v34, v34, v44, v45
	v_max3_f32 v34, v34, v46, v47
	v_max3_f32 v34, v34, v48, v49
	v_bitop3_b32 v19, v19, s74, v69 bitop3:0xe4
	v_bitop3_b32 v20, v20, s74, v70 bitop3:0xe4
	v_max3_f32 v34, v34, v18, v19
	v_bitop3_b32 v21, v21, s74, v71 bitop3:0xe4
	v_bitop3_b32 v22, v22, s74, v72 bitop3:0xe4
	v_max3_f32 v34, v34, v20, v21
	v_bitop3_b32 v23, v23, s74, v73 bitop3:0xe4
	v_bitop3_b32 v24, v24, s74, v74 bitop3:0xe4
	v_max3_f32 v34, v34, v22, v23
	v_bitop3_b32 v25, v25, s74, v75 bitop3:0xe4
	v_bitop3_b32 v26, v26, s74, v76 bitop3:0xe4
	v_max3_f32 v34, v34, v24, v25
	v_bitop3_b32 v27, v27, s74, v77 bitop3:0xe4
	v_bitop3_b32 v28, v28, s74, v78 bitop3:0xe4
	v_max3_f32 v34, v34, v26, v27
	v_bitop3_b32 v29, v29, s74, v79 bitop3:0xe4
	v_bitop3_b32 v30, v30, s74, v80 bitop3:0xe4
	v_max3_f32 v34, v34, v28, v29
	v_bitop3_b32 v31, v31, s74, v81 bitop3:0xe4
	v_bitop3_b32 v32, v32, s74, v82 bitop3:0xe4
	v_max3_f32 v34, v34, v30, v31
	v_bitop3_b32 v33, v33, s74, v66 bitop3:0xe4
	v_max3_f32 v34, v34, v32, v33
	v_mov_b32_e32 v66, v34
	s_nop 1
	v_permlane32_swap_b32_e32 v34, v66
	v_max_f32_e32 v66, v66, v66
	v_max_f32_e32 v34, v34, v34
	v_max_f32_e32 v34, v34, v66
	v_add_f32_e32 v66, 0x7149f2ca, v34
	v_mul_f32_e32 v66, 0x3db504f3, v66
	v_max_f32_e32 v34, 0xf149f2ca, v34
	v_cmp_ge_f32_e32 vcc, s75, v66
	v_sub_f32_e32 v66, 0xf149f2ca, v34
	v_mul_f32_e32 v66, 0x3e0293ee, v66
	s_cmp_eq_u64 vcc, exec
	v_exp_f32_e32 v66, v66
	s_cselect_b64 vcc, -1, 0
	v_cndmask_b32_e32 v206, v34, v203, vcc
	v_mul_f32_e32 v34, 0xbe0293ee, v206
	v_mov_b32_e32 v67, v34
	v_cndmask_b32_e64 v177, v66, 1.0, vcc
	v_fmamk_f32 v66, v68, 0x3e0293ee, v34
	v_fmamk_f32 v35, v35, 0x3e0293ee, v34
	v_fmamk_f32 v36, v36, 0x3e0293ee, v34
	v_fmamk_f32 v37, v37, 0x3e0293ee, v34
	v_fmamk_f32 v38, v38, 0x3e0293ee, v34
	v_fmamk_f32 v39, v39, 0x3e0293ee, v34
	v_fmamk_f32 v40, v40, 0x3e0293ee, v34
	v_fmamk_f32 v41, v41, 0x3e0293ee, v34
	v_fmamk_f32 v42, v42, 0x3e0293ee, v34
	v_fmamk_f32 v43, v43, 0x3e0293ee, v34
	v_fmamk_f32 v44, v44, 0x3e0293ee, v34
	v_fmamk_f32 v45, v45, 0x3e0293ee, v34
	v_fmamk_f32 v46, v46, 0x3e0293ee, v34
	v_fmamk_f32 v47, v47, 0x3e0293ee, v34
	v_fmamk_f32 v48, v48, 0x3e0293ee, v34
	v_fmac_f32_e32 v67, 0x3e0293ee, v49
	v_exp_f32_e32 v219, v66
	v_exp_f32_e32 v220, v35
	v_exp_f32_e32 v221, v36
	v_exp_f32_e32 v222, v37
	v_exp_f32_e32 v223, v38
	v_exp_f32_e32 v225, v39
	v_exp_f32_e32 v224, v40
	v_exp_f32_e32 v226, v41
	v_exp_f32_e32 v211, v42
	v_exp_f32_e32 v212, v43
	v_exp_f32_e32 v213, v44
	v_exp_f32_e32 v215, v45
	v_exp_f32_e32 v214, v46
	v_exp_f32_e32 v216, v47
	v_exp_f32_e32 v217, v48
	v_exp_f32_e32 v218, v67
	s_lshl_b32 s36, s83, 8
	v_pk_fma_f32 v[152:153], v[32:33], s[14:15], v[34:35] op_sel_hi:[1,0,0]
	v_pk_fma_f32 v[156:157], v[30:31], s[14:15], v[34:35] op_sel_hi:[1,0,0]
	v_pk_fma_f32 v[160:161], v[28:29], s[14:15], v[34:35] op_sel_hi:[1,0,0]
	v_pk_fma_f32 v[150:151], v[26:27], s[14:15], v[34:35] op_sel_hi:[1,0,0]
	v_pk_fma_f32 v[154:155], v[24:25], s[14:15], v[34:35] op_sel_hi:[1,0,0]
	v_pk_fma_f32 v[158:159], v[22:23], s[14:15], v[34:35] op_sel_hi:[1,0,0]
	v_pk_fma_f32 v[192:193], v[20:21], s[14:15], v[34:35] op_sel_hi:[1,0,0]
	v_pk_fma_f32 v[194:195], v[18:19], s[14:15], v[34:35] op_sel_hi:[1,0,0]
	s_and_b32 s36, s36, 0xffffc000
	v_mov_b64_e32 v[48:49], v[16:17]
	v_mov_b64_e32 v[32:33], v[16:17]
	v_or_b32_e32 v179, s36, v254
	v_mov_b64_e32 v[46:47], v[14:15]
	v_mov_b64_e32 v[44:45], v[12:13]
	v_mov_b64_e32 v[42:43], v[10:11]
	v_mov_b64_e32 v[40:41], v[8:9]
	v_mov_b64_e32 v[38:39], v[6:7]
	v_mov_b64_e32 v[36:37], v[4:5]
	v_mov_b64_e32 v[34:35], v[2:3]
	v_mov_b64_e32 v[30:31], v[14:15]
	v_mov_b64_e32 v[28:29], v[12:13]
	v_mov_b64_e32 v[26:27], v[10:11]
	v_mov_b64_e32 v[24:25], v[8:9]
	v_mov_b64_e32 v[22:23], v[6:7]
	v_mov_b64_e32 v[20:21], v[4:5]
	v_mov_b64_e32 v[18:19], v[2:3]
	v_mul_f32_e32 v190, 0xbe0293ee, v206
	s_mov_b32 s76, 0
	v_readfirstlane_b32 s77, v0
	s_nop 3
	s_lshr_b32 s77, s77, 8
	s_cmp_eq_u32 s77, 0
	s_cbranch_scc1 .Lp5_lead
	s_setprio 1
	s_barrier

; #define SBAR() __builtin_amdgcn_sched_barrier(0)
; #define SLOAD_H(Kp, Vp, k0) do { S.st_v0 = load8(ROW(Vp, k0, sr)); S.st_v1 = load8(ROW(Vp, k0, 32 + sr));              \
;                          S.st_k0 = load8(ROW(Kp, k0, sr)); S.st_k1 = load8(ROW(Kp, k0, 32 + sr)); } while (0)
; #define RESC(a) do { if (__any((a) < 1.f)) { if (hi == 0) al_l[r32] = (a); asm volatile("s_waitcnt lgkmcnt(0)" ::: "memory");              \
;                      for (int d_ = 0; d_ < 4; ++d_) for (int r = 0; r < 16; ++r) o[d_][r] *= al_l[crow(r, hi)]; } } while (0)
; #define MASKT(P0_, P1_) sel_mask_tile(P0_, P1_, mw.x, mw.y, hi)
; #define SEAM_K0() do { VMWN(NQL); SWRITE_HK(0); SBAR(); } while (0)
; __device__ __forceinline__ void attn_block(const BlockRef& cur, const BlockRef& nxt, char* lds, Seam& S) {
;     ...
;     mw = LDMASK(NT - 1);
;     SBAR(); qkt<1>(pB0, pB1, K_lds, r32, hi, S.qr); SBAR();
;     SLOAD_H(nxt.K, nxt.V, 0); SBAR();
; #pragma unroll
;     for (int d0 = 0; d0 < 8; ++d0) S.qr[d0] = load8(nxt.Q + (size_t)(wid * QBLK + r32) * LD + d0 * 16 + hi * 8);
;     SBAR();
;     finishSM(pA0, pA1, alA, l_reg, pa0, pa1, pa2, pa3); SBAR();
;     pv_tile<0>(o, vb0, pa0, pa1, pa2, pa3);
;     MASKT(pB0, pB1); partialSM(pB0, pB1, m_reg, mnB, alB); __syncthreads(); RESC(alB);
;     finishSM(pB0, pB1, alB, l_reg, pa0, pa1, pa2, pa3); SBAR(); pv_tile<1>(o, vb0, pa0, pa1, pa2, pa3);
;     SBAR(); SEAM_K0();
;     if (hi == 0) li_l[r32] = l_reg; asm volatile("s_waitcnt lgkmcnt(0)" ::: "memory");
.Lp5_exit:
	s_waitcnt vmcnt(0)
	s_setprio 0
	s_cmp_lg_u32 s77, 0
	s_cbranch_scc1 .Lp5_exit_b
	s_waitcnt lgkmcnt(0)
	s_barrier
